# v18 + TRX hand-written prologue weight transposes (LDS staged, prefetched)
# baseline (speedup 1.0000x reference)
; #define LAS __attribute__((address_space(3)))
; template <bool PERMIN> __device__ __forceinline__ void transpose_item(const float* W, int K, int N, bf16* WT, LAS float* scr, int item, int lane) {
;     const int nblk = N / 32, kb = item / nblk, nb = item % nblk, k0 = 64 * kb, n0 = 32 * nb;
; #pragma unroll 8
;     for (int i = 0; i < 32; ++i) { const int kk = 2 * i + (lane >> 5); scr[kk * 33 + (lane & 31)] = W[(size_t)(k0 + kk) * N + n0 + (lane & 31)]; }
;     asm volatile("s_waitcnt lgkmcnt(0)" ::: "memory");
;     int r0 = n0;
;     if (PERMIN) { const int cl = n0 & 255; r0 = (n0 & ~255) + 128 * ((cl >> 5) & 1) + 32 * (cl >> 6); }
; __global__ void __launch_bounds__(NTHR, 2) trunk_fwd(Args a) {
;     ...
;         for (int it = gw; it < DEPTH * I_L; it += ngw) { const int l = it / I_L; int r = it % I_L;
;             if (r < I_IN) { transpose_item<true>(a.w_in + (size_t)l * DM * DIN, DM, DIN, WT_IN + (size_t)l * DIN * DM, scr, r, lane); continue; } r -= I_IN;
;             if (r < I_OUT) { transpose_item<true>(a.w_out + (size_t)l * DM * DM, DM, DM, WT_OUT + (size_t)l * DM * DM, scr, r, lane); continue; } r -= I_OUT;
;             if (r < I_1) { transpose_item<true>(a.w_ff1 + (size_t)l * DM * DFF, DM, DFF, WT_1 + (size_t)l * DFF * DM, scr, r, lane); continue; } r -= I_1;
;             transpose_item<true>(a.w_ff2 + (size_t)l * DFF * DM, DFF, DM, WT_2 + (size_t)l * DM * DFF, scr, r, lane); }
.Ltrx_entry:
	v_mbcnt_lo_u32_b32 v5, -1, 0
	v_mbcnt_hi_u32_b32 v5, -1, v5
	v_readfirstlane_b32 s4, v212
	v_lshrrev_b32_e32 v6, 3, v5
	v_and_b32_e32 v7, 7, v5
	v_lshlrev_b32_e32 v7, 4, v7
	s_nop 1
	s_lshr_b32 s4, s4, 6
	s_lshl_b32 s4, s4, 14
	v_mul_u32_u24_e32 v8, 0x84, v6
	v_add3_u32 v8, v8, v7, s4
	v_mul_u32_u24_e32 v9, 66, v7
	v_lshl_add_u32 v9, v6, 2, v9
	v_add_u32_e32 v9, s4, v9
	s_cmp_lt_u32 s12, 0x5a00
	s_cbranch_scc0 .Ltrx_done
	s_mov_b32 s4, 0
	s_mov_b32 s5, s12
	s_cmp_ge_u32 s5, 0x1680
	s_cselect_b32 s6, 0x1680, 0
	s_cselect_b32 s7, 1, 0
	s_sub_u32 s5, s5, s6
	s_add_u32 s4, s4, s7
	s_cmp_ge_u32 s5, 0x1680
	s_cselect_b32 s6, 0x1680, 0
	s_cselect_b32 s7, 1, 0
	s_sub_u32 s5, s5, s6
	s_add_u32 s4, s4, s7
	s_cmp_ge_u32 s5, 0x1680
	s_cselect_b32 s6, 0x1680, 0
	s_cselect_b32 s7, 1, 0
	s_sub_u32 s5, s5, s6
	s_add_u32 s4, s4, s7
	s_cmp_lt_u32 s5, 0x480
	s_cbranch_scc0 .Ltrx_p_c1
	s_mul_i32 s6, s4, 0x900000
	s_add_u32 s14, s80, s6
	s_addc_u32 s15, s81, 0
	s_mul_i32 s6, s4, 0x480000
	s_add_u32 s16, s94, s6
	s_addc_u32 s17, s95, 0
	s_mul_hi_u32 s8, s5, 0x38e38e4
	s_mul_i32 s6, s8, 72
	s_sub_u32 s9, s5, s6
	s_movk_i32 s10, 0x900
	s_movk_i32 s11, 0x400
	s_branch .Ltrx_p_join
.Ltrx_p_c1:
	s_cmp_lt_u32 s5, 0x680
	s_cbranch_scc0 .Ltrx_p_c2
	s_sub_u32 s5, s5, 0x480
	s_lshl_b32 s6, s4, 22
	s_add_u32 s14, s18, s6
	s_addc_u32 s15, s19, 0
	s_lshl_b32 s6, s4, 21
	s_add_u32 s6, s6, 0x1200000
	s_add_u32 s16, s94, s6
	s_addc_u32 s17, s95, 0
	s_lshr_b32 s8, s5, 5
	s_and_b32 s9, s5, 31
	s_movk_i32 s10, 0x400
	s_movk_i32 s11, 0x400
	s_branch .Ltrx_p_join
.Ltrx_p_c2:
	s_cmp_lt_u32 s5, 0xe80
	s_cbranch_scc0 .Ltrx_p_c3
	s_sub_u32 s5, s5, 0x680
	s_lshl_b32 s6, s4, 24
	s_add_u32 s14, s24, s6
	s_addc_u32 s15, s25, 0
	s_lshl_b32 s6, s4, 23
	s_add_u32 s6, s6, 0x1a00000
	s_add_u32 s16, s94, s6
	s_addc_u32 s17, s95, 0
	s_lshr_b32 s8, s5, 7
	s_and_b32 s9, s5, 127
	s_movk_i32 s10, 0x1000
	s_movk_i32 s11, 0x400
	s_branch .Ltrx_p_join
.Ltrx_p_c3:
	s_sub_u32 s5, s5, 0xe80
	s_lshl_b32 s6, s4, 24
	s_add_u32 s14, s26, s6
	s_addc_u32 s15, s27, 0
	s_lshl_b32 s6, s4, 23
	s_add_u32 s6, s6, 0x3a00000
	s_add_u32 s16, s94, s6
	s_addc_u32 s17, s95, 0
	s_lshr_b32 s8, s5, 5
	s_and_b32 s9, s5, 31
	s_movk_i32 s10, 0x400
	s_movk_i32 s11, 0x1000
.Ltrx_p_join:
	s_lshl_b32 s8, s8, 6
	s_lshl_b32 s9, s9, 5
	s_mul_i32 s6, s8, s10
	s_add_u32 s6, s6, s9
	s_lshl_b32 s6, s6, 2
	s_add_u32 s14, s14, s6
	s_addc_u32 s15, s15, 0
	s_and_b32 s6, s9, 0xff
	s_lshr_b32 s7, s6, 5
	s_and_b32 s7, s7, 1
	s_lshl_b32 s7, s7, 7
	s_lshr_b32 s6, s6, 6
	s_lshl_b32 s6, s6, 5
	s_andn2_b32 s9, s9, 0xff
	s_add_u32 s9, s9, s7
	s_add_u32 s9, s9, s6
	s_mul_i32 s6, s9, s11
	s_add_u32 s6, s6, s8
	s_lshl_b32 s6, s6, 1
	s_add_u32 s40, s16, s6
	s_addc_u32 s41, s17, 0
	s_lshl_b32 s42, s11, 1
	s_lshl_b32 s6, s10, 2
	v_mul_u32_u24_e32 v10, s6, v6
	v_add_u32_e32 v10, v10, v7
	s_lshl_b32 s6, s10, 5
	global_load_dwordx4 v[16:19], v10, s[14:15]
	v_add_u32_e32 v10, s6, v10
	global_load_dwordx4 v[20:23], v10, s[14:15]
	v_add_u32_e32 v10, s6, v10
	global_load_dwordx4 v[24:27], v10, s[14:15]
	v_add_u32_e32 v10, s6, v10
	global_load_dwordx4 v[28:31], v10, s[14:15]
	v_add_u32_e32 v10, s6, v10
	global_load_dwordx4 v[32:35], v10, s[14:15]
	v_add_u32_e32 v10, s6, v10
	global_load_dwordx4 v[36:39], v10, s[14:15]
	v_add_u32_e32 v10, s6, v10
	global_load_dwordx4 v[40:43], v10, s[14:15]
	v_add_u32_e32 v10, s6, v10
	global_load_dwordx4 v[44:47], v10, s[14:15]
.Ltrx_loop:
	s_add_u32 s13, s12, s38
	s_cmp_lt_u32 s13, 0x5a00
	s_cbranch_scc0 .Ltrx_last_0
	s_mov_b32 s4, 0
	s_mov_b32 s5, s13
	s_cmp_ge_u32 s5, 0x1680
	s_cselect_b32 s6, 0x1680, 0
	s_cselect_b32 s7, 1, 0
	s_sub_u32 s5, s5, s6
	s_add_u32 s4, s4, s7
	s_cmp_ge_u32 s5, 0x1680
	s_cselect_b32 s6, 0x1680, 0
	s_cselect_b32 s7, 1, 0
	s_sub_u32 s5, s5, s6
	s_add_u32 s4, s4, s7
	s_cmp_ge_u32 s5, 0x1680
	s_cselect_b32 s6, 0x1680, 0
	s_cselect_b32 s7, 1, 0
	s_sub_u32 s5, s5, s6
	s_add_u32 s4, s4, s7
	s_cmp_lt_u32 s5, 0x480
	s_cbranch_scc0 .Ltrx_l0_c1
	s_mul_i32 s6, s4, 0x900000
	s_add_u32 s14, s80, s6
	s_addc_u32 s15, s81, 0
	s_mul_i32 s6, s4, 0x480000
	s_add_u32 s16, s94, s6
	s_addc_u32 s17, s95, 0
	s_mul_hi_u32 s8, s5, 0x38e38e4
	s_mul_i32 s6, s8, 72
	s_sub_u32 s9, s5, s6
	s_movk_i32 s10, 0x900
	s_movk_i32 s11, 0x400
	s_branch .Ltrx_l0_join

; #define LAS __attribute__((address_space(3)))
; __device__ __forceinline__ unsigned pk2(float lo, float hi) { return f2bf(lo) | (f2bf(hi) << 16); }
; template <bool PERMIN> __device__ __forceinline__ void transpose_item(const float* W, int K, int N, bf16* WT, LAS float* scr, int item, int lane) {
;     const int nblk = N / 32, kb = item / nblk, nb = item % nblk, k0 = 64 * kb, n0 = 32 * nb;
; #pragma unroll 8
;     for (int i = 0; i < 32; ++i) { const int kk = 2 * i + (lane >> 5); scr[kk * 33 + (lane & 31)] = W[(size_t)(k0 + kk) * N + n0 + (lane & 31)]; }
;     asm volatile("s_waitcnt lgkmcnt(0)" ::: "memory");
;     int r0 = n0;
;     if (PERMIN) { const int cl = n0 & 255; r0 = (n0 & ~255) + 128 * ((cl >> 5) & 1) + 32 * (cl >> 6); }
;     const int c = lane & 7;
; #pragma unroll
;     for (int j = 0; j < 4; ++j) { const int n = (lane >> 3) + 8 * j; const LAS float* s = scr + (8 * c) * 33 + n;
;         v4u o; o.x = pk2(s[0 * 33], s[1 * 33]); o.y = pk2(s[2 * 33], s[3 * 33]); o.z = pk2(s[4 * 33], s[5 * 33]); o.w = pk2(s[6 * 33], s[7 * 33]);
;         *(v4u*)(WT + (size_t)(r0 + n) * K + k0 + 8 * c) = o; }
.Ltrx_l0_join:
	s_lshl_b32 s8, s8, 6
	s_lshl_b32 s9, s9, 5
	s_mul_i32 s6, s8, s10
	s_add_u32 s6, s6, s9
	s_lshl_b32 s6, s6, 2
	s_add_u32 s14, s14, s6
	s_addc_u32 s15, s15, 0
	s_and_b32 s6, s9, 0xff
	s_lshr_b32 s7, s6, 5
	s_and_b32 s7, s7, 1
	s_lshl_b32 s7, s7, 7
	s_lshr_b32 s6, s6, 6
	s_lshl_b32 s6, s6, 5
	s_andn2_b32 s9, s9, 0xff
	s_add_u32 s9, s9, s7
	s_add_u32 s9, s9, s6
	s_mul_i32 s6, s9, s11
	s_add_u32 s6, s6, s8
	s_lshl_b32 s6, s6, 1
	s_add_u32 s44, s16, s6
	s_addc_u32 s45, s17, 0
	s_lshl_b32 s46, s11, 1
	s_lshl_b32 s6, s10, 2
	v_mul_u32_u24_e32 v10, s6, v6
	v_add_u32_e32 v10, v10, v7
	s_lshl_b32 s6, s10, 5
	global_load_dwordx4 v[48:51], v10, s[14:15]
	v_add_u32_e32 v10, s6, v10
	global_load_dwordx4 v[52:55], v10, s[14:15]
	v_add_u32_e32 v10, s6, v10
	global_load_dwordx4 v[56:59], v10, s[14:15]
	v_add_u32_e32 v10, s6, v10
	global_load_dwordx4 v[60:63], v10, s[14:15]
	v_add_u32_e32 v10, s6, v10
	global_load_dwordx4 v[64:67], v10, s[14:15]
	v_add_u32_e32 v10, s6, v10
	global_load_dwordx4 v[68:71], v10, s[14:15]
	v_add_u32_e32 v10, s6, v10
	global_load_dwordx4 v[72:75], v10, s[14:15]
	v_add_u32_e32 v10, s6, v10
	global_load_dwordx4 v[76:79], v10, s[14:15]
	s_waitcnt vmcnt(8)
	s_branch .Ltrx_proc_0

; #define LAS __attribute__((address_space(3)))
; __device__ __forceinline__ unsigned pk2(float lo, float hi) { return f2bf(lo) | (f2bf(hi) << 16); }
; template <bool PERMIN> __device__ __forceinline__ void transpose_item(const float* W, int K, int N, bf16* WT, LAS float* scr, int item, int lane) {
;     ...
;     for (int i = 0; i < 32; ++i) { const int kk = 2 * i + (lane >> 5); scr[kk * 33 + (lane & 31)] = W[(size_t)(k0 + kk) * N + n0 + (lane & 31)]; }
;     asm volatile("s_waitcnt lgkmcnt(0)" ::: "memory");
;     int r0 = n0;
;     if (PERMIN) { const int cl = n0 & 255; r0 = (n0 & ~255) + 128 * ((cl >> 5) & 1) + 32 * (cl >> 6); }
;     const int c = lane & 7;
; #pragma unroll
;     for (int j = 0; j < 4; ++j) { const int n = (lane >> 3) + 8 * j; const LAS float* s = scr + (8 * c) * 33 + n;
;         v4u o; o.x = pk2(s[0 * 33], s[1 * 33]); o.y = pk2(s[2 * 33], s[3 * 33]); o.z = pk2(s[4 * 33], s[5 * 33]); o.w = pk2(s[6 * 33], s[7 * 33]);
;         *(v4u*)(WT + (size_t)(r0 + n) * K + k0 + 8 * c) = o; }
;     asm volatile("s_waitcnt lgkmcnt(0)" ::: "memory");
; __global__ void __launch_bounds__(NTHR, 2) trunk_fwd(Args a) {
;     ...
;         for (int it = gw; it < DEPTH * I_L; it += ngw) { const int l = it / I_L; int r = it % I_L;
;             if (r < I_IN) { transpose_item<true>(a.w_in + (size_t)l * DM * DIN, DM, DIN, WT_IN + (size_t)l * DIN * DM, scr, r, lane); continue; } r -= I_IN;
;             if (r < I_OUT) { transpose_item<true>(a.w_out + (size_t)l * DM * DM, DM, DM, WT_OUT + (size_t)l * DM * DM, scr, r, lane); continue; } r -= I_OUT;
;             if (r < I_1) { transpose_item<true>(a.w_ff1 + (size_t)l * DM * DFF, DM, DFF, WT_1 + (size_t)l * DFF * DM, scr, r, lane); continue; } r -= I_1;
;             transpose_item<true>(a.w_ff2 + (size_t)l * DFF * DM, DFF, DM, WT_2 + (size_t)l * DM * DFF, scr, r, lane); }
.Ltrx_proc_0:
	ds_write_b32 v8, v16 offset:0
	ds_write_b32 v8, v17 offset:4
	ds_write_b32 v8, v18 offset:8
	ds_write_b32 v8, v19 offset:12
	ds_write_b32 v8, v20 offset:1056
	ds_write_b32 v8, v21 offset:1060
	ds_write_b32 v8, v22 offset:1064
	ds_write_b32 v8, v23 offset:1068
	ds_write_b32 v8, v24 offset:2112
	ds_write_b32 v8, v25 offset:2116
	ds_write_b32 v8, v26 offset:2120
	ds_write_b32 v8, v27 offset:2124
	ds_write_b32 v8, v28 offset:3168
	ds_write_b32 v8, v29 offset:3172
	ds_write_b32 v8, v30 offset:3176
	ds_write_b32 v8, v31 offset:3180
	ds_write_b32 v8, v32 offset:4224
	ds_write_b32 v8, v33 offset:4228
	ds_write_b32 v8, v34 offset:4232
	ds_write_b32 v8, v35 offset:4236
	ds_write_b32 v8, v36 offset:5280
	ds_write_b32 v8, v37 offset:5284
	ds_write_b32 v8, v38 offset:5288
	ds_write_b32 v8, v39 offset:5292
	ds_write_b32 v8, v40 offset:6336
	ds_write_b32 v8, v41 offset:6340
	ds_write_b32 v8, v42 offset:6344
	ds_write_b32 v8, v43 offset:6348
	ds_write_b32 v8, v44 offset:7392
	ds_write_b32 v8, v45 offset:7396
	ds_write_b32 v8, v46 offset:7400
	ds_write_b32 v8, v47 offset:7404
	s_waitcnt lgkmcnt(0)
	ds_read_b32 v96, v9 offset:0
	ds_read_b32 v97, v9 offset:132
	ds_read_b32 v98, v9 offset:264
	ds_read_b32 v99, v9 offset:396
	ds_read_b32 v100, v9 offset:528
	ds_read_b32 v101, v9 offset:660
	ds_read_b32 v102, v9 offset:792
	ds_read_b32 v103, v9 offset:924
	ds_read_b32 v104, v9 offset:32
	ds_read_b32 v105, v9 offset:164
	ds_read_b32 v106, v9 offset:296
	ds_read_b32 v107, v9 offset:428
	ds_read_b32 v108, v9 offset:560
	ds_read_b32 v109, v9 offset:692
	ds_read_b32 v110, v9 offset:824
	ds_read_b32 v111, v9 offset:956
	v_mul_lo_u32 v11, s42, v6
	v_add_u32_e32 v11, v11, v7
	s_lshl_b32 s6, s42, 3
	s_waitcnt lgkmcnt(8)
	v_cvt_pk_bf16_f32 v128, v96, v97
	v_cvt_pk_bf16_f32 v129, v98, v99
	v_cvt_pk_bf16_f32 v130, v100, v101
	v_cvt_pk_bf16_f32 v131, v102, v103
	ds_read_b32 v112, v9 offset:64
	ds_read_b32 v113, v9 offset:196
	ds_read_b32 v114, v9 offset:328
	ds_read_b32 v115, v9 offset:460
	ds_read_b32 v116, v9 offset:592
	ds_read_b32 v117, v9 offset:724
	ds_read_b32 v118, v9 offset:856
	ds_read_b32 v119, v9 offset:988
	global_store_dwordx4 v11, v[128:131], s[40:41]
	v_add_u32_e32 v11, s6, v11
	s_waitcnt lgkmcnt(8)
	v_cvt_pk_bf16_f32 v132, v104, v105
	v_cvt_pk_bf16_f32 v133, v106, v107
	v_cvt_pk_bf16_f32 v134, v108, v109
	v_cvt_pk_bf16_f32 v135, v110, v111
	ds_read_b32 v120, v9 offset:96
	ds_read_b32 v121, v9 offset:228
	ds_read_b32 v122, v9 offset:360
	ds_read_b32 v123, v9 offset:492
	ds_read_b32 v124, v9 offset:624
	ds_read_b32 v125, v9 offset:756
	ds_read_b32 v126, v9 offset:888
	ds_read_b32 v127, v9 offset:1020
	global_store_dwordx4 v11, v[132:135], s[40:41]
	v_add_u32_e32 v11, s6, v11
	s_waitcnt lgkmcnt(8)
	v_cvt_pk_bf16_f32 v136, v112, v113
	v_cvt_pk_bf16_f32 v137, v114, v115
	v_cvt_pk_bf16_f32 v138, v116, v117
	v_cvt_pk_bf16_f32 v139, v118, v119
	global_store_dwordx4 v11, v[136:139], s[40:41]
	v_add_u32_e32 v11, s6, v11
	s_waitcnt lgkmcnt(0)
	v_cvt_pk_bf16_f32 v140, v120, v121
	v_cvt_pk_bf16_f32 v141, v122, v123
	v_cvt_pk_bf16_f32 v142, v124, v125
	v_cvt_pk_bf16_f32 v143, v126, v127
	global_store_dwordx4 v11, v[140:143], s[40:41]
	s_mov_b32 s12, s13
	s_cmp_lt_u32 s12, 0x5a00
	s_cbranch_scc0 .Ltrx_done
	s_add_u32 s13, s12, s38
	s_cmp_lt_u32 s13, 0x5a00
	s_cbranch_scc0 .Ltrx_last_1
	s_mov_b32 s4, 0
	s_mov_b32 s5, s13
	s_cmp_ge_u32 s5, 0x1680
	s_cselect_b32 s6, 0x1680, 0
	s_cselect_b32 s7, 1, 0
	s_sub_u32 s5, s5, s6
	s_add_u32 s4, s4, s7
	s_cmp_ge_u32 s5, 0x1680
	s_cselect_b32 s6, 0x1680, 0
	s_cselect_b32 s7, 1, 0
	s_sub_u32 s5, s5, s6
	s_add_u32 s4, s4, s7
	s_cmp_ge_u32 s5, 0x1680
	s_cselect_b32 s6, 0x1680, 0
	s_cselect_b32 s7, 1, 0
	s_sub_u32 s5, s5, s6
	s_add_u32 s4, s4, s7
	s_cmp_lt_u32 s5, 0x480
	s_cbranch_scc0 .Ltrx_l1_c1
	s_mul_i32 s6, s4, 0x900000
	s_add_u32 s14, s80, s6
	s_addc_u32 s15, s81, 0
	s_mul_i32 s6, s4, 0x480000
	s_add_u32 s16, s94, s6
	s_addc_u32 s17, s95, 0
	s_mul_hi_u32 s8, s5, 0x38e38e4
	s_mul_i32 s6, s8, 72
	s_sub_u32 s9, s5, s6
	s_movk_i32 s10, 0x900
	s_movk_i32 s11, 0x400
	s_branch .Ltrx_l1_join

; #define LAS __attribute__((address_space(3)))
; __device__ __forceinline__ unsigned pk2(float lo, float hi) { return f2bf(lo) | (f2bf(hi) << 16); }
; template <bool PERMIN> __device__ __forceinline__ void transpose_item(const float* W, int K, int N, bf16* WT, LAS float* scr, int item, int lane) {
;     const int nblk = N / 32, kb = item / nblk, nb = item % nblk, k0 = 64 * kb, n0 = 32 * nb;
; #pragma unroll 8
;     for (int i = 0; i < 32; ++i) { const int kk = 2 * i + (lane >> 5); scr[kk * 33 + (lane & 31)] = W[(size_t)(k0 + kk) * N + n0 + (lane & 31)]; }
;     asm volatile("s_waitcnt lgkmcnt(0)" ::: "memory");
;     int r0 = n0;
;     if (PERMIN) { const int cl = n0 & 255; r0 = (n0 & ~255) + 128 * ((cl >> 5) & 1) + 32 * (cl >> 6); }
;     const int c = lane & 7;
; #pragma unroll
;     for (int j = 0; j < 4; ++j) { const int n = (lane >> 3) + 8 * j; const LAS float* s = scr + (8 * c) * 33 + n;
;         v4u o; o.x = pk2(s[0 * 33], s[1 * 33]); o.y = pk2(s[2 * 33], s[3 * 33]); o.z = pk2(s[4 * 33], s[5 * 33]); o.w = pk2(s[6 * 33], s[7 * 33]);
;         *(v4u*)(WT + (size_t)(r0 + n) * K + k0 + 8 * c) = o; }
.Ltrx_l1_join:
	s_lshl_b32 s8, s8, 6
	s_lshl_b32 s9, s9, 5
	s_mul_i32 s6, s8, s10
	s_add_u32 s6, s6, s9
	s_lshl_b32 s6, s6, 2
	s_add_u32 s14, s14, s6
	s_addc_u32 s15, s15, 0
	s_and_b32 s6, s9, 0xff
	s_lshr_b32 s7, s6, 5
	s_and_b32 s7, s7, 1
	s_lshl_b32 s7, s7, 7
	s_lshr_b32 s6, s6, 6
	s_lshl_b32 s6, s6, 5
	s_andn2_b32 s9, s9, 0xff
	s_add_u32 s9, s9, s7
	s_add_u32 s9, s9, s6
	s_mul_i32 s6, s9, s11
	s_add_u32 s6, s6, s8
	s_lshl_b32 s6, s6, 1
	s_add_u32 s40, s16, s6
	s_addc_u32 s41, s17, 0
	s_lshl_b32 s42, s11, 1
	s_lshl_b32 s6, s10, 2
	v_mul_u32_u24_e32 v10, s6, v6
	v_add_u32_e32 v10, v10, v7
	s_lshl_b32 s6, s10, 5
	global_load_dwordx4 v[16:19], v10, s[14:15]
	v_add_u32_e32 v10, s6, v10
	global_load_dwordx4 v[20:23], v10, s[14:15]
	v_add_u32_e32 v10, s6, v10
	global_load_dwordx4 v[24:27], v10, s[14:15]
	v_add_u32_e32 v10, s6, v10
	global_load_dwordx4 v[28:31], v10, s[14:15]
	v_add_u32_e32 v10, s6, v10
	global_load_dwordx4 v[32:35], v10, s[14:15]
	v_add_u32_e32 v10, s6, v10
	global_load_dwordx4 v[36:39], v10, s[14:15]
	v_add_u32_e32 v10, s6, v10
	global_load_dwordx4 v[40:43], v10, s[14:15]
	v_add_u32_e32 v10, s6, v10
	global_load_dwordx4 v[44:47], v10, s[14:15]
	s_waitcnt vmcnt(8)
	s_branch .Ltrx_proc_1

; #define LAS __attribute__((address_space(3)))
; __device__ __forceinline__ unsigned pk2(float lo, float hi) { return f2bf(lo) | (f2bf(hi) << 16); }
; template <bool PERMIN> __device__ __forceinline__ void transpose_item(const float* W, int K, int N, bf16* WT, LAS float* scr, int item, int lane) {
;     ...
;     for (int i = 0; i < 32; ++i) { const int kk = 2 * i + (lane >> 5); scr[kk * 33 + (lane & 31)] = W[(size_t)(k0 + kk) * N + n0 + (lane & 31)]; }
;     asm volatile("s_waitcnt lgkmcnt(0)" ::: "memory");
;     int r0 = n0;
;     if (PERMIN) { const int cl = n0 & 255; r0 = (n0 & ~255) + 128 * ((cl >> 5) & 1) + 32 * (cl >> 6); }
;     const int c = lane & 7;
; #pragma unroll
;     for (int j = 0; j < 4; ++j) { const int n = (lane >> 3) + 8 * j; const LAS float* s = scr + (8 * c) * 33 + n;
;         v4u o; o.x = pk2(s[0 * 33], s[1 * 33]); o.y = pk2(s[2 * 33], s[3 * 33]); o.z = pk2(s[4 * 33], s[5 * 33]); o.w = pk2(s[6 * 33], s[7 * 33]);
;         *(v4u*)(WT + (size_t)(r0 + n) * K + k0 + 8 * c) = o; }
;     asm volatile("s_waitcnt lgkmcnt(0)" ::: "memory");
.Ltrx_proc_1:
	ds_write_b32 v8, v48 offset:0
	ds_write_b32 v8, v49 offset:4
	ds_write_b32 v8, v50 offset:8
	ds_write_b32 v8, v51 offset:12
	ds_write_b32 v8, v52 offset:1056
	ds_write_b32 v8, v53 offset:1060
	ds_write_b32 v8, v54 offset:1064
	ds_write_b32 v8, v55 offset:1068
	ds_write_b32 v8, v56 offset:2112
	ds_write_b32 v8, v57 offset:2116
	ds_write_b32 v8, v58 offset:2120
	ds_write_b32 v8, v59 offset:2124
	ds_write_b32 v8, v60 offset:3168
	ds_write_b32 v8, v61 offset:3172
	ds_write_b32 v8, v62 offset:3176
	ds_write_b32 v8, v63 offset:3180
	ds_write_b32 v8, v64 offset:4224
	ds_write_b32 v8, v65 offset:4228
	ds_write_b32 v8, v66 offset:4232
	ds_write_b32 v8, v67 offset:4236
	ds_write_b32 v8, v68 offset:5280
	ds_write_b32 v8, v69 offset:5284
	ds_write_b32 v8, v70 offset:5288
	ds_write_b32 v8, v71 offset:5292
	ds_write_b32 v8, v72 offset:6336
	ds_write_b32 v8, v73 offset:6340
	ds_write_b32 v8, v74 offset:6344
	ds_write_b32 v8, v75 offset:6348
	ds_write_b32 v8, v76 offset:7392
	ds_write_b32 v8, v77 offset:7396
	ds_write_b32 v8, v78 offset:7400
	ds_write_b32 v8, v79 offset:7404
	s_waitcnt lgkmcnt(0)
	ds_read_b32 v96, v9 offset:0
	ds_read_b32 v97, v9 offset:132
	ds_read_b32 v98, v9 offset:264
	ds_read_b32 v99, v9 offset:396
	ds_read_b32 v100, v9 offset:528
	ds_read_b32 v101, v9 offset:660
	ds_read_b32 v102, v9 offset:792
	ds_read_b32 v103, v9 offset:924
	ds_read_b32 v104, v9 offset:32
	ds_read_b32 v105, v9 offset:164
	ds_read_b32 v106, v9 offset:296
	ds_read_b32 v107, v9 offset:428
	ds_read_b32 v108, v9 offset:560
	ds_read_b32 v109, v9 offset:692
	ds_read_b32 v110, v9 offset:824
	ds_read_b32 v111, v9 offset:956
	v_mul_lo_u32 v11, s46, v6
	v_add_u32_e32 v11, v11, v7
	s_lshl_b32 s6, s46, 3
	s_waitcnt lgkmcnt(8)
	v_cvt_pk_bf16_f32 v128, v96, v97
	v_cvt_pk_bf16_f32 v129, v98, v99
	v_cvt_pk_bf16_f32 v130, v100, v101
	v_cvt_pk_bf16_f32 v131, v102, v103
	ds_read_b32 v112, v9 offset:64
	ds_read_b32 v113, v9 offset:196
	ds_read_b32 v114, v9 offset:328
	ds_read_b32 v115, v9 offset:460
	ds_read_b32 v116, v9 offset:592
	ds_read_b32 v117, v9 offset:724
	ds_read_b32 v118, v9 offset:856
	ds_read_b32 v119, v9 offset:988
	global_store_dwordx4 v11, v[128:131], s[44:45]
	v_add_u32_e32 v11, s6, v11
	s_waitcnt lgkmcnt(8)
	v_cvt_pk_bf16_f32 v132, v104, v105
	v_cvt_pk_bf16_f32 v133, v106, v107
	v_cvt_pk_bf16_f32 v134, v108, v109
	v_cvt_pk_bf16_f32 v135, v110, v111
	ds_read_b32 v120, v9 offset:96
	ds_read_b32 v121, v9 offset:228
	ds_read_b32 v122, v9 offset:360
	ds_read_b32 v123, v9 offset:492
	ds_read_b32 v124, v9 offset:624
	ds_read_b32 v125, v9 offset:756
	ds_read_b32 v126, v9 offset:888
	ds_read_b32 v127, v9 offset:1020
	global_store_dwordx4 v11, v[132:135], s[44:45]
	v_add_u32_e32 v11, s6, v11
	s_waitcnt lgkmcnt(8)
	v_cvt_pk_bf16_f32 v136, v112, v113
	v_cvt_pk_bf16_f32 v137, v114, v115
	v_cvt_pk_bf16_f32 v138, v116, v117
	v_cvt_pk_bf16_f32 v139, v118, v119
	global_store_dwordx4 v11, v[136:139], s[44:45]
	v_add_u32_e32 v11, s6, v11
	s_waitcnt lgkmcnt(0)
	v_cvt_pk_bf16_f32 v140, v120, v121
	v_cvt_pk_bf16_f32 v141, v122, v123
	v_cvt_pk_bf16_f32 v142, v124, v125
	v_cvt_pk_bf16_f32 v143, v126, v127
	global_store_dwordx4 v11, v[140:143], s[44:45]
	s_mov_b32 s12, s13
	s_cmp_lt_u32 s12, 0x5a00
	s_cbranch_scc0 .Ltrx_done
	s_branch .Ltrx_loop
.Ltrx_done:
	s_waitcnt vmcnt(0) lgkmcnt(0)
; __global__ void __launch_bounds__(NTHR, 2) trunk_fwd(Args a) {
;     ...
;         const int gt = bx * NTHR + tid, ngt = G * NTHR;
;         for (int i = gt; i < SEQ * 32; i += ngt) { const int t = i >> 5, d = i & 31; const float inv = powf(10000.0f, -(float)(d & 15) / 16.0f); const float ang = (float)(d < 16 ? (t >> 6) : (t & 63)) * inv;
;             ROPE[2 * i] = cosf(ang); ROPE[2 * i + 1] = sinf(ang); }
.LBB0_50:
	s_lshl_b32 s4, s79, 9
	v_writelane_b32 v253, s4, 24
	v_add_u32_e32 v6, s4, v4
	s_mov_b32 s4, 0x20000
	s_lshl_b32 s50, s60, 9
	v_cmp_gt_i32_e32 vcc, s4, v6
	s_and_saveexec_b64 s[12:13], vcc
	s_cbranch_execz .LBB0_61
	v_and_b32_e32 v1, 15, v4
	v_cvt_f32_ubyte0_e32 v1, v1
	v_mul_f32_e32 v1, 0xbd800000, v1
	v_mov_b32_e32 v3, 0x461c4000
	v_cmp_eq_f32_e32 vcc, 0, v1
	s_mov_b32 s4, 0x3f2aaaab
	s_movk_i32 s6, 0x204
	v_cndmask_b32_e64 v3, v3, 1.0, vcc
	v_frexp_mant_f32_e32 v5, v3
	v_cmp_gt_f32_e64 s[4:5], s4, v5
	s_mov_b32 s8, 0x42b17218
	s_mov_b32 s7, 0x7f800000
	v_cndmask_b32_e64 v7, 1.0, 2.0, s[4:5]
	v_mul_f32_e32 v5, v5, v7
	v_add_f32_e32 v7, 1.0, v5
	v_rcp_f32_e32 v16, v7
	v_add_f32_e32 v8, -1.0, v7
	v_add_f32_e32 v9, -1.0, v5
	v_sub_f32_e32 v8, v5, v8
	v_mul_f32_e32 v5, v9, v16
	v_mul_f32_e32 v10, v7, v5
	v_fma_f32 v12, v5, v7, -v10
	v_fmac_f32_e32 v12, v5, v8
	v_add_f32_e32 v8, v10, v12
	v_sub_f32_e32 v11, v9, v8
	v_pk_add_f32 v[14:15], v[8:9], v[10:11] neg_lo:[0,1] neg_hi:[0,1]
	v_mov_b32_e32 v13, v8
	v_pk_add_f32 v[8:9], v[14:15], v[12:13] neg_lo:[0,1] neg_hi:[0,1]
	s_add_u32 s14, s94, 0x5b00000
	v_add_f32_e32 v7, v8, v9
	v_add_f32_e32 v7, v11, v7
	v_mul_f32_e32 v7, v16, v7
	v_add_f32_e32 v8, v5, v7
	v_sub_f32_e32 v5, v8, v5
	v_sub_f32_e32 v5, v7, v5
	v_mul_f32_e32 v7, v8, v8
	v_fma_f32 v9, v8, v8, -v7
	v_add_f32_e32 v10, v5, v5
	v_fmac_f32_e32 v9, v8, v10
	v_add_f32_e32 v10, v7, v9
	v_mov_b32_e32 v11, 0x3e91f4c4
	v_fmac_f32_e32 v11, 0x3e76c4e1, v10
	v_fmaak_f32 v11, v10, v11, 0x3ecccdef
	v_sub_f32_e32 v7, v10, v7
	v_sub_f32_e32 v7, v9, v7
	v_mul_f32_e32 v9, v10, v11
	v_fma_f32 v12, v10, v11, -v9
	v_fmac_f32_e32 v12, v7, v11
	v_add_f32_e32 v11, v9, v12
	v_add_f32_e32 v13, 0x3f2aaaaa, v11
	v_sub_f32_e32 v9, v11, v9
	v_sub_f32_e32 v9, v12, v9
	v_add_f32_e32 v12, 0xbf2aaaaa, v13
	v_add_f32_e32 v9, 0x31739010, v9
	v_sub_f32_e32 v11, v11, v12
	v_pk_mul_f32 v[14:15], v[8:9], v[10:11]
	v_pk_add_f32 v[16:17], v[8:9], v[10:11]
	v_fma_f32 v12, v10, v8, -v14
	v_fmac_f32_e32 v12, v10, v5
	v_mov_b32_e32 v15, v17
	v_fmac_f32_e32 v12, v7, v8
	v_pk_add_f32 v[10:11], v[14:15], v[12:13]
	s_addc_u32 s15, s95, 0
	v_sub_f32_e32 v9, v13, v11
	v_add_f32_e32 v9, v17, v9
	v_cvt_f64_f32_e32 v[16:17], v3
	v_frexp_exp_i32_f64_e32 v3, v[16:17]
	v_subbrev_co_u32_e64 v3, s[4:5], 0, v3, s[4:5]
	v_cvt_f32_i32_e32 v3, v3
	v_sub_f32_e32 v7, v10, v14
	v_sub_f32_e32 v7, v12, v7
	v_pk_mul_f32 v[12:13], v[10:11], v[10:11] op_sel:[0,1] op_sel_hi:[1,0]
	s_mov_b32 s4, 0x3f317218
	v_fma_f32 v14, v10, v11, -v12
	v_fmac_f32_e32 v14, v10, v9
	v_mul_f32_e32 v10, 0x3f317218, v3
	v_fmac_f32_e32 v14, v7, v11
	v_fma_f32 v7, v3, s4, -v10
	v_fmamk_f32 v16, v3, 0xb102e308, v7
	v_ldexp_f32 v17, v8, 1
	v_add_f32_e32 v11, v12, v14
	v_pk_add_f32 v[8:9], v[10:11], v[16:17]
	v_mov_b32_e32 v18, v11
	v_mov_b32_e32 v19, v9
	v_mov_b32_e32 v13, v17
	v_pk_add_f32 v[12:13], v[18:19], v[12:13] neg_lo:[0,1] neg_hi:[0,1]
	v_mov_b32_e32 v15, v11
	v_ldexp_f32 v3, v5, 1
	v_pk_add_f32 v[12:13], v[14:15], v[12:13] neg_lo:[0,1] neg_hi:[0,1]
	v_mov_b32_e32 v17, v8
	v_add_f32_e32 v3, v3, v12
	v_add_f32_e32 v11, v3, v13
	v_pk_add_f32 v[12:13], v[8:9], v[10:11] neg_lo:[0,1] neg_hi:[0,1]
	v_pk_add_f32 v[14:15], v[8:9], v[10:11]
	v_mov_b32_e32 v10, v11
	v_mov_b32_e32 v13, v15
	v_pk_add_f32 v[18:19], v[16:17], v[12:13] neg_lo:[0,1] neg_hi:[0,1]
	v_pk_add_f32 v[12:13], v[16:17], v[12:13]
	v_mov_b32_e32 v11, v8
	v_pk_add_f32 v[16:17], v[12:13], v[8:9] op_sel:[1,0] op_sel_hi:[0,1] neg_lo:[0,1] neg_hi:[0,1]
	v_pk_add_f32 v[20:21], v[14:15], v[16:17] op_sel_hi:[1,0] neg_lo:[0,1] neg_hi:[0,1]
	v_mov_b32_e32 v14, v15
	v_mov_b32_e32 v15, v13
	v_pk_mov_b32 v[16:17], v[8:9], v[16:17] op_sel:[1,0]
	v_mov_b32_e32 v20, v18
	v_pk_add_f32 v[14:15], v[14:15], v[16:17] neg_lo:[0,1] neg_hi:[0,1]
	v_mov_b32_e32 v19, v13
	v_pk_add_f32 v[8:9], v[10:11], v[14:15] neg_lo:[0,1] neg_hi:[0,1]
	s_lshl_b32 s20, s60, 10
	v_pk_add_f32 v[10:11], v[20:21], v[8:9]
	s_mov_b64 s[16:17], 0
	v_pk_add_f32 v[14:15], v[10:11], v[10:11] op_sel:[0,1] op_sel_hi:[1,0]
	s_brev_b32 s21, 18
	v_pk_add_f32 v[12:13], v[12:13], v[14:15] op_sel:[1,0] op_sel_hi:[0,1]
	v_mov_b32_e32 v11, v12
	v_pk_add_f32 v[16:17], v[10:11], v[18:19] neg_lo:[0,1] neg_hi:[0,1]
	v_mov_b32_e32 v9, v14
	v_sub_f32_e32 v3, v10, v16
	v_pk_add_f32 v[8:9], v[8:9], v[16:17] neg_lo:[0,1] neg_hi:[0,1]
	v_sub_f32_e32 v3, v18, v3
	v_add_f32_e32 v3, v8, v3
	v_add_f32_e32 v3, v3, v9
	v_add_f32_e32 v5, v12, v3
	v_sub_f32_e32 v7, v5, v12
	v_sub_f32_e32 v3, v3, v7
	v_mul_f32_e32 v7, v1, v5
	v_fma_f32 v5, v1, v5, -v7
	v_fmac_f32_e32 v5, v1, v3
	v_add_f32_e32 v3, v7, v5
	v_cmp_class_f32_e64 s[4:5], v7, s6
	v_sub_f32_e32 v8, v3, v7
	v_sub_f32_e32 v5, v5, v8
	v_cndmask_b32_e64 v3, v3, v7, s[4:5]
	v_mov_b32_e32 v7, 0x37000000
	v_cmp_eq_f32_e64 s[4:5], s8, v3
	s_mov_b32 s22, 0xfe5163ab
	s_mov_b32 s23, 0x3c439041
	v_cndmask_b32_e64 v7, 0, v7, s[4:5]
	v_sub_f32_e32 v8, v3, v7
	s_mov_b32 s4, 0x3fb8aa3b
	v_mul_f32_e32 v9, 0x3fb8aa3b, v8
	v_fma_f32 v10, v8, s4, -v9
	v_rndne_f32_e32 v11, v9
	v_fmamk_f32 v10, v8, 0x32a5705f, v10
	v_sub_f32_e32 v9, v9, v11
	v_add_f32_e32 v9, v9, v10
	v_exp_f32_e32 v9, v9
	v_cvt_i32_f32_e32 v10, v11
	v_cmp_neq_f32_e64 s[4:5], |v3|, s7
	s_mov_b32 s24, 0xdb629599
	s_mov_b32 s25, 0xf534ddc0
	v_cndmask_b32_e64 v3, 0, v5, s[4:5]
	s_mov_b32 s4, 0xc2ce8ed0
	v_ldexp_f32 v5, v9, v10
	v_cmp_ngt_f32_e64 s[4:5], s4, v8
	v_add_f32_e32 v3, v7, v3
	v_mov_b32_e32 v7, 0x7f800000
	v_cndmask_b32_e64 v5, 0, v5, s[4:5]
	v_cmp_nlt_f32_e64 s[4:5], s8, v8
	v_mov_b32_e32 v9, 0
	s_mov_b32 s26, 0xfc2757d1
	v_cndmask_b32_e64 v5, v7, v5, s[4:5]
	v_fma_f32 v3, v5, v3, v5
	v_cmp_class_f32_e64 s[4:5], v5, s6
	s_mov_b32 s27, 0x4e441529
	s_mov_b32 s28, 0xa2f9836e
	v_cndmask_b32_e64 v3, v3, v5, s[4:5]
	v_cmp_neq_f32_e64 s[4:5], v1, |v1|
	s_mov_b32 s29, 0x3fc90fda
	s_mov_b32 s30, 0x3f22f983
	v_cndmask_b32_e64 v5, v7, 0, s[4:5]
	v_cndmask_b32_e64 v5, v5, 1.0, vcc
	v_cmp_class_f32_e64 s[4:5], v1, s6
	s_mov_b32 s31, 0xbfc90fda
	v_mov_b32_e32 v7, 0xbab64f3b
	v_cndmask_b32_e64 v1, |v3|, v5, s[4:5]
	v_lshlrev_b32_e32 v3, 1, v4
	v_lshl_add_u32 v4, s79, 10, v3
	v_mov_b32_e32 v3, 0x3c0881c4
	s_brev_b32 s34, 1
	s_movk_i32 s35, 0x1f8
	s_mov_b32 s36, 0x1ffff
	v_not_b32_e32 v12, 63
	v_not_b32_e32 v13, 31
	v_mov_b32_e32 v14, 0x7fc00000
	v_mov_b32_e32 v15, v6
	s_branch .LBB0_53
